# LN loops A and B2: (1+scale) of the hoisted modulation vectors computed once at reload, 8 per-row v_pk_add removed in each
# baseline (speedup 1.0000x reference)
.LBB0_1220:
	s_waitcnt vmcnt(7)
	s_add_i32 s3, s3, 1
	s_addk_i32 s10, 0x100
	v_mov_b64_e32 v[110:111], v[62:63]
	v_mov_b64_e32 v[106:107], v[58:59]
	v_mov_b64_e32 v[102:103], v[54:55]
	v_mov_b64_e32 v[90:91], v[50:51]
	v_pk_fma_f32 v[64:65], v[68:69], v[74:75], v[64:65]
	s_cmp_lg_u32 s11, s3
	v_mov_b64_e32 v[108:109], v[60:61]
	v_mov_b64_e32 v[104:105], v[56:57]
	v_mov_b64_e32 v[100:101], v[52:53]
	v_mov_b64_e32 v[88:89], v[48:49]
	v_pk_fma_f32 v[66:67], v[70:71], v[72:73], v[66:67]
	v_cvt_pk_bf16_f32 v64, v64, v65
	s_nop 0
	v_cvt_pk_bf16_f32 v65, v66, v67
	global_store_dwordx2 v[92:93], v[64:65], off offset:1536
	s_cbranch_scc0 .LBB0_1235

.Lmy_lnh_a_reload:
	global_load_dwordx4 v[178:181], v144, s[8:9]
	global_load_dwordx4 v[182:185], v144, s[8:9] offset:1024
	global_load_dwordx4 v[186:189], v144, s[14:15]
	global_load_dwordx4 v[190:193], v159, s[14:15]
	global_load_dwordx4 v[212:215], v144, s[8:9] offset:2048
	global_load_dwordx4 v[216:219], v144, s[8:9] offset:3072
	global_load_dwordx4 v[222:225], v160, s[14:15]
	global_load_dwordx4 v[226:229], v161, s[14:15]
	s_waitcnt vmcnt(0)
	v_pk_add_f32 v[186:187], v[186:187], 1.0 op_sel_hi:[1,0]
	v_pk_add_f32 v[188:189], v[188:189], 1.0 op_sel_hi:[1,0]
	v_pk_add_f32 v[190:191], v[190:191], 1.0 op_sel_hi:[1,0]
	v_pk_add_f32 v[192:193], v[192:193], 1.0 op_sel_hi:[1,0]
	v_pk_add_f32 v[222:223], v[222:223], 1.0 op_sel_hi:[1,0]
	v_pk_add_f32 v[224:225], v[224:225], 1.0 op_sel_hi:[1,0]
	v_pk_add_f32 v[226:227], v[226:227], 1.0 op_sel_hi:[1,0]
	v_pk_add_f32 v[228:229], v[228:229], 1.0 op_sel_hi:[1,0]

.LBB0_1229:
	s_waitcnt vmcnt(9)
	s_lshl_b64 s[12:13], s[12:13], 10
	v_pk_fma_f32 v[94:95], v[98:99], v[108:109], v[94:95]
	v_pk_fma_f32 v[92:93], v[96:97], v[112:113], v[92:93]
	v_mov_b32_e32 v114, v104
	v_mov_b32_e32 v115, v110
	v_mov_b32_e32 v107, v106
	v_cvt_pk_bf16_f32 v96, v92, v93
	v_cvt_pk_bf16_f32 v97, v94, v95
	v_lshl_add_u64 v[92:93], s[12:13], 1, v[156:157]
	v_mov_b32_e32 v94, v106
	v_mov_b32_e32 v95, v106
	v_mov_b32_e32 v104, v111
	global_store_dwordx2 v[92:93], v[96:97], off
	v_pk_mul_f32 v[96:97], v[104:105], v[94:95]
	v_pk_mul_f32 v[98:99], v[114:115], v[106:107]
	v_pk_fma_f32 v[96:97], v[6:7], v[96:97], v[14:15]
	s_and_b64 vcc, exec, s[8:9]
	v_pk_fma_f32 v[98:99], v[4:5], v[98:99], v[12:13]
	s_cbranch_vccnz .LBB0_1231
	v_pk_mul_f32 v[110:111], v[96:97], s[58:59] op_sel_hi:[1,0]
	v_pk_mul_f32 v[108:109], v[98:99], s[58:59] op_sel_hi:[1,0]
	global_store_dwordx4 v144, v[108:111], s[16:17] offset:1024
.LBB0_1231:
	s_waitcnt vmcnt(9)
	v_pk_fma_f32 v[80:81], v[84:85], v[98:99], v[80:81]
	v_pk_fma_f32 v[82:83], v[86:87], v[96:97], v[82:83]
	v_cvt_pk_bf16_f32 v80, v80, v81
	s_and_b64 vcc, exec, s[8:9]
	v_cvt_pk_bf16_f32 v81, v82, v83
	global_store_dwordx2 v[92:93], v[80:81], off offset:512
	v_pk_mul_f32 v[80:81], v[102:103], v[94:95]
	v_pk_mul_f32 v[82:83], v[100:101], v[106:107]
	v_pk_fma_f32 v[80:81], v[18:19], v[80:81], v[26:27]
	v_pk_fma_f32 v[82:83], v[16:17], v[82:83], v[24:25]
	s_cbranch_vccnz .LBB0_1233
	v_pk_mul_f32 v[86:87], v[80:81], s[58:59] op_sel_hi:[1,0]
	v_pk_mul_f32 v[84:85], v[82:83], s[58:59] op_sel_hi:[1,0]
	global_store_dwordx4 v144, v[84:87], s[16:17] offset:2048
.LBB0_1233:
	s_waitcnt vmcnt(7)
	v_pk_fma_f32 v[72:73], v[76:77], v[82:83], v[72:73]
	v_pk_fma_f32 v[74:75], v[78:79], v[80:81], v[74:75]
	v_cvt_pk_bf16_f32 v72, v72, v73
	s_and_b64 vcc, exec, s[8:9]
	v_cvt_pk_bf16_f32 v73, v74, v75
	global_store_dwordx2 v[92:93], v[72:73], off offset:1024
	v_mov_b32_e32 v72, v106
	v_mov_b32_e32 v73, v106
	v_pk_mul_f32 v[72:73], v[90:91], v[72:73]
	v_pk_mul_f32 v[74:75], v[88:89], v[106:107]
	v_pk_fma_f32 v[72:73], v[22:23], v[72:73], v[30:31]
	v_pk_fma_f32 v[74:75], v[20:21], v[74:75], v[28:29]
	s_cbranch_vccnz .LBB0_1220
	v_pk_mul_f32 v[78:79], v[72:73], s[58:59] op_sel_hi:[1,0]
	v_pk_mul_f32 v[76:77], v[74:75], s[58:59] op_sel_hi:[1,0]
	global_store_dwordx4 v144, v[76:79], s[16:17] offset:3072
	s_branch .LBB0_1220

.LBB0_1469:
	s_waitcnt vmcnt(7)
	s_add_i32 s3, s3, 1
	v_mov_b64_e32 v[102:103], v[62:63]
	v_mov_b64_e32 v[106:107], v[58:59]
	v_mov_b64_e32 v[110:111], v[54:55]
	v_mov_b64_e32 v[90:91], v[50:51]
	v_pk_fma_f32 v[64:65], v[68:69], v[74:75], v[64:65]
	s_cmp_eq_u32 s3, s13
	v_mov_b64_e32 v[100:101], v[60:61]
	v_mov_b64_e32 v[104:105], v[56:57]
	v_mov_b64_e32 v[108:109], v[52:53]
	v_mov_b64_e32 v[88:89], v[48:49]
	v_pk_fma_f32 v[66:67], v[70:71], v[72:73], v[66:67]
	v_cvt_pk_bf16_f32 v64, v64, v65
	s_nop 0
	v_cvt_pk_bf16_f32 v65, v66, v67
	global_store_dwordx2 v[92:93], v[64:65], off offset:1536
	s_cbranch_scc1 .LBB0_1489

.Lmy_lnh_b_reload:
	global_load_dwordx4 v[178:181], v130, s[8:9]
	global_load_dwordx4 v[182:185], v130, s[8:9] offset:1024
	global_load_dwordx4 v[186:189], v130, s[16:17]
	global_load_dwordx4 v[190:193], v131, s[16:17]
	global_load_dwordx4 v[212:215], v130, s[8:9] offset:2048
	global_load_dwordx4 v[216:219], v130, s[8:9] offset:3072
	global_load_dwordx4 v[222:225], v132, s[16:17]
	global_load_dwordx4 v[226:229], v133, s[16:17]
	s_waitcnt vmcnt(0)
	v_pk_add_f32 v[186:187], v[186:187], 1.0 op_sel_hi:[1,0]
	v_pk_add_f32 v[188:189], v[188:189], 1.0 op_sel_hi:[1,0]
	v_pk_add_f32 v[190:191], v[190:191], 1.0 op_sel_hi:[1,0]
	v_pk_add_f32 v[192:193], v[192:193], 1.0 op_sel_hi:[1,0]
	v_pk_add_f32 v[222:223], v[222:223], 1.0 op_sel_hi:[1,0]
	v_pk_add_f32 v[224:225], v[224:225], 1.0 op_sel_hi:[1,0]
	v_pk_add_f32 v[226:227], v[226:227], 1.0 op_sel_hi:[1,0]
	v_pk_add_f32 v[228:229], v[228:229], 1.0 op_sel_hi:[1,0]

.LBB0_1483:
	s_waitcnt vmcnt(9)
	s_lshl_b64 s[14:15], s[14:15], 10
	v_pk_fma_f32 v[94:95], v[98:99], v[108:109], v[94:95]
	v_pk_fma_f32 v[92:93], v[96:97], v[110:111], v[92:93]
	v_mov_b32_e32 v101, v100
	v_cvt_pk_bf16_f32 v96, v92, v93
	v_cvt_pk_bf16_f32 v97, v94, v95
	v_lshl_add_u64 v[92:93], s[14:15], 1, v[122:123]
	v_mov_b32_e32 v94, v100
	v_mov_b32_e32 v95, v100
	global_store_dwordx2 v[92:93], v[96:97], off
	v_pk_mul_f32 v[96:97], v[106:107], v[94:95]
	v_pk_mul_f32 v[98:99], v[112:113], v[100:101]
	v_pk_fma_f32 v[96:97], v[6:7], v[96:97], v[14:15]
	s_and_b64 vcc, exec, s[8:9]
	v_pk_fma_f32 v[98:99], v[4:5], v[98:99], v[12:13]
	s_cbranch_vccnz .LBB0_1485
	v_pk_mul_f32 v[108:109], v[96:97], s[58:59] op_sel_hi:[1,0]
	v_pk_mul_f32 v[106:107], v[98:99], s[58:59] op_sel_hi:[1,0]
	global_store_dwordx4 v130, v[106:109], s[18:19] offset:1024
.LBB0_1485:
	s_waitcnt vmcnt(9)
	v_pk_fma_f32 v[80:81], v[84:85], v[98:99], v[80:81]
	v_pk_fma_f32 v[82:83], v[86:87], v[96:97], v[82:83]
	v_cvt_pk_bf16_f32 v80, v80, v81
	s_and_b64 vcc, exec, s[8:9]
	v_cvt_pk_bf16_f32 v81, v82, v83
	global_store_dwordx2 v[92:93], v[80:81], off offset:512
	v_pk_mul_f32 v[80:81], v[102:103], v[94:95]
	v_pk_mul_f32 v[82:83], v[104:105], v[100:101]
	v_pk_fma_f32 v[80:81], v[18:19], v[80:81], v[26:27]
	v_pk_fma_f32 v[82:83], v[16:17], v[82:83], v[24:25]
	s_cbranch_vccnz .LBB0_1487
	v_pk_mul_f32 v[86:87], v[80:81], s[58:59] op_sel_hi:[1,0]
	v_pk_mul_f32 v[84:85], v[82:83], s[58:59] op_sel_hi:[1,0]
	global_store_dwordx4 v130, v[84:87], s[18:19] offset:2048
.LBB0_1487:
	s_waitcnt vmcnt(7)
	v_pk_fma_f32 v[72:73], v[76:77], v[82:83], v[72:73]
	v_pk_fma_f32 v[74:75], v[78:79], v[80:81], v[74:75]
	v_cvt_pk_bf16_f32 v72, v72, v73
	s_and_b64 vcc, exec, s[8:9]
	v_cvt_pk_bf16_f32 v73, v74, v75
	global_store_dwordx2 v[92:93], v[72:73], off offset:1024
	v_mov_b32_e32 v72, v100
	v_mov_b32_e32 v73, v100
	v_pk_mul_f32 v[72:73], v[90:91], v[72:73]
	v_pk_mul_f32 v[74:75], v[88:89], v[100:101]
	v_pk_fma_f32 v[72:73], v[22:23], v[72:73], v[30:31]
	v_pk_fma_f32 v[74:75], v[20:21], v[74:75], v[28:29]
	s_cbranch_vccnz .LBB0_1469
	v_pk_mul_f32 v[78:79], v[72:73], s[58:59] op_sel_hi:[1,0]
	v_pk_mul_f32 v[76:77], v[74:75], s[58:59] op_sel_hi:[1,0]
	global_store_dwordx4 v130, v[76:79], s[18:19] offset:3072
	s_branch .LBB0_1469
